# attention KV loop: dropped no-op staged vmcnt waits after the full drain and XNACK-only pads between back-to-back loads
# speedup vs baseline: 1.0046x; 1.0023x over previous
.LBB0_563:
	s_add_i32 s16, s13, -1
	ds_read_b128 v[64:67], v187 offset:57344
	ds_read_b128 v[68:71], v202 offset:57344
	ds_read_b128 v[220:223], v189 offset:57344
	ds_read_b128 v[232:235], v201 offset:57344
	v_add_f32_e32 v178, 0, v136
	v_add_f32_e32 v178, v230, v178
	s_waitcnt lgkmcnt(3)
	v_mfma_f32_32x32x16_bf16 v[80:95], v[64:67], v[96:99], 0
	v_add_f32_e32 v178, v137, v178
	v_add_f32_e32 v178, v229, v178
	v_add_f32_e32 v178, v138, v178
	v_add_f32_e32 v178, v228, v178
	v_add_f32_e32 v178, v139, v178
	v_add_f32_e32 v178, v213, v178
	v_add_f32_e32 v178, v144, v178
	s_waitcnt lgkmcnt(2)
	v_mfma_f32_32x32x16_bf16 v[64:79], v[68:71], v[96:99], 0
	v_add_f32_e32 v178, v147, v178
	v_add_f32_e32 v178, v145, v178
	v_add_f32_e32 v178, v146, v178
	v_exp_f32_e32 v132, v132
	v_add_f32_e32 v178, v141, v178
	v_exp_f32_e32 v133, v133
	v_add_f32_e32 v178, v143, v178
	s_waitcnt lgkmcnt(1)
	v_mfma_f32_32x32x16_bf16 v[80:95], v[220:223], v[100:103], v[80:95]
	v_exp_f32_e32 v134, v134
	v_add_f32_e32 v178, v140, v178
	v_exp_f32_e32 v135, v135
	v_add_f32_e32 v178, v142, v178
	v_exp_f32_e32 v124, v124
	v_add_f32_e32 v178, v132, v178
	v_exp_f32_e32 v125, v125
	s_waitcnt lgkmcnt(0)
	v_mfma_f32_32x32x16_bf16 v[64:79], v[232:235], v[100:103], v[64:79]
	ds_read_b128 v[220:223], v190 offset:57344
	ds_read_b128 v[232:235], v209 offset:57344
	v_add_f32_e32 v178, v133, v178
	v_exp_f32_e32 v126, v126
	v_add_f32_e32 v178, v134, v178
	v_exp_f32_e32 v127, v127
	v_add_f32_e32 v178, v135, v178
	v_exp_f32_e32 v128, v128
	s_waitcnt lgkmcnt(1)
	v_mfma_f32_32x32x16_bf16 v[80:95], v[220:223], v[104:107], v[80:95]
	v_add_f32_e32 v178, v124, v178
	v_exp_f32_e32 v129, v129
	v_add_f32_e32 v178, v125, v178
	v_exp_f32_e32 v130, v130
	v_add_f32_e32 v178, v126, v178
	v_exp_f32_e32 v131, v131
	v_add_f32_e32 v178, v127, v178
	s_waitcnt lgkmcnt(0)
	v_mfma_f32_32x32x16_bf16 v[64:79], v[232:235], v[104:107], v[64:79]
	ds_read_b128 v[220:223], v191 offset:57344
	ds_read_b128 v[232:235], v212 offset:57344
	v_exp_f32_e32 v120, v120
	v_add_f32_e32 v178, v128, v178
	v_exp_f32_e32 v121, v121
	v_add_f32_e32 v178, v129, v178
	v_exp_f32_e32 v122, v122
	v_add_f32_e32 v178, v130, v178
	s_waitcnt lgkmcnt(1)
	v_mfma_f32_32x32x16_bf16 v[80:95], v[220:223], v[108:111], v[80:95]
	v_exp_f32_e32 v123, v123
	v_add_f32_e32 v178, v131, v178
	v_add_f32_e32 v178, v120, v178
	v_add_f32_e32 v178, v121, v178
	v_add_f32_e32 v178, v122, v178
	v_add_f32_e32 v231, v123, v178
	s_waitcnt lgkmcnt(0)
	v_mfma_f32_32x32x16_bf16 v[64:79], v[232:235], v[108:111], v[64:79]
	ds_read_b128 v[220:223], v192 offset:57344
	ds_read_b128 v[232:235], v211 offset:57344
	s_waitcnt lgkmcnt(1)
	v_mfma_f32_32x32x16_bf16 v[80:95], v[220:223], v[112:115], v[80:95]
	s_waitcnt lgkmcnt(0)
	v_mfma_f32_32x32x16_bf16 v[64:79], v[232:235], v[112:115], v[64:79]
	ds_read_b128 v[220:223], v193 offset:57344
	ds_read_b128 v[232:235], v210 offset:57344
	s_waitcnt lgkmcnt(1)
	v_mfma_f32_32x32x16_bf16 v[80:95], v[220:223], v[116:119], v[80:95]
	s_waitcnt lgkmcnt(0)
	v_mfma_f32_32x32x16_bf16 v[64:79], v[232:235], v[116:119], v[64:79]
	ds_read_b128 v[220:223], v194 offset:57344
	ds_read_b128 v[232:235], v208 offset:57344
	ds_read_b128 v[236:239], v171
	s_waitcnt lgkmcnt(0)
	v_mfma_f32_32x32x16_bf16 v[80:95], v[220:223], v[236:239], v[80:95]
	v_mfma_f32_32x32x16_bf16 v[64:79], v[232:235], v[236:239], v[64:79]
	ds_read_b128 v[220:223], v195 offset:57344
	ds_read_b128 v[232:235], v207 offset:57344
	ds_read_b128 v[236:239], v171 offset:1024
	s_waitcnt lgkmcnt(0)
	v_mfma_f32_32x32x16_bf16 v[80:95], v[220:223], v[236:239], v[80:95]
	v_mfma_f32_32x32x16_bf16 v[64:79], v[232:235], v[236:239], v[64:79]
	ds_read_b128 v[220:223], v196 offset:57344
	ds_read_b128 v[232:235], v206 offset:57344
	ds_read_b128 v[236:239], v171 offset:2048
	s_waitcnt lgkmcnt(0)
	v_mfma_f32_32x32x16_bf16 v[80:95], v[220:223], v[236:239], v[80:95]
	v_mfma_f32_32x32x16_bf16 v[64:79], v[232:235], v[236:239], v[64:79]
	ds_read_b128 v[220:223], v197 offset:57344
	ds_read_b128 v[232:235], v205 offset:57344
	ds_read_b128 v[236:239], v171 offset:3072
	s_waitcnt lgkmcnt(0)
	v_mfma_f32_32x32x16_bf16 v[80:95], v[220:223], v[236:239], v[80:95]
	v_mfma_f32_32x32x16_bf16 v[64:79], v[232:235], v[236:239], v[64:79]
	ds_read_b128 v[220:223], v199 offset:57344
	ds_read_b128 v[232:235], v204 offset:57344
	ds_read_b128 v[236:239], v171 offset:4096
	s_waitcnt lgkmcnt(0)
	v_mfma_f32_32x32x16_bf16 v[80:95], v[220:223], v[236:239], v[80:95]
	v_mfma_f32_32x32x16_bf16 v[64:79], v[232:235], v[236:239], v[64:79]
	ds_read_b128 v[220:223], v198 offset:57344
	ds_read_b128 v[232:235], v203 offset:57344
	ds_read_b128 v[236:239], v171 offset:5120
	v_cvt_pk_bf16_f32 v136, v136, v230
	v_cvt_pk_bf16_f32 v137, v137, v229
	v_cvt_pk_bf16_f32 v138, v138, v228
	v_cvt_pk_bf16_f32 v139, v139, v213
	v_cvt_pk_bf16_f32 v144, v144, v147
	v_cvt_pk_bf16_f32 v145, v145, v146
	s_waitcnt lgkmcnt(0)
	v_mfma_f32_32x32x16_bf16 v[80:95], v[220:223], v[236:239], v[80:95]
	v_cvt_pk_bf16_f32 v146, v141, v143
	v_cvt_pk_bf16_f32 v147, v140, v142
	v_cvt_pk_bf16_f32 v220, v132, v133
	v_cvt_pk_bf16_f32 v221, v134, v135
	v_cvt_pk_bf16_f32 v222, v124, v125
	v_cvt_pk_bf16_f32 v223, v126, v127
	v_permlane32_swap_b32_e32 v136, v138
	v_mfma_f32_32x32x16_bf16 v[64:79], v[232:235], v[236:239], v[64:79]
	v_mov_b32_e32 v233, v231
	v_cvt_pk_bf16_f32 v234, v128, v129
	v_cvt_pk_bf16_f32 v235, v130, v131
	v_cvt_pk_bf16_f32 v236, v120, v121
	s_nop 1
	v_permlane32_swap_b32_e32 v231, v233
	v_cvt_pk_bf16_f32 v237, v122, v123
	v_permlane32_swap_b32_e32 v234, v236
	v_permlane32_swap_b32_e32 v137, v139
	v_permlane32_swap_b32_e32 v144, v146
	v_permlane32_swap_b32_e32 v145, v147
	v_permlane32_swap_b32_e32 v220, v222
	v_permlane32_swap_b32_e32 v221, v223
	v_permlane32_swap_b32_e32 v235, v237
	s_sub_i32 s4, s14, 64
	s_cmp_lt_u32 s16, 3
	s_cselect_b32 s4, s15, s4
	s_ashr_i32 s5, s4, 31
	s_lshl_b64 s[76:77], s[4:5], 11
	s_mul_hi_i32 s79, s4, s87
	s_mul_i32 s78, s4, s87
	v_lshl_add_u64 v[120:121], v[148:149], 0, s[76:77]
	v_lshl_add_u64 v[124:125], v[156:157], 0, s[76:77]
	v_lshl_add_u64 v[130:131], v[150:151], 0, s[78:79]
	v_lshl_add_u64 v[134:135], v[152:153], 0, s[78:79]
	v_lshl_add_u64 v[140:141], v[154:155], 0, s[78:79]
	global_load_dwordx4 v[120:123], v[120:121], off
	global_load_dwordx4 v[124:127], v[124:125], off
	global_load_dwordx4 v[128:131], v[130:131], off
	global_load_dwordx4 v[132:135], v[134:135], off
	global_load_dwordx4 v[140:143], v[140:141], off
	ds_read_b64_tr_b16 v[238:239], v172 offset:0
	ds_read_b64_tr_b16 v[240:241], v172 offset:0x800
	ds_read_b64_tr_b16 v[242:243], v172 offset:0x1000
	ds_read_b64_tr_b16 v[244:245], v172 offset:0x1800
	ds_read_b64_tr_b16 v[246:247], v172 offset:0x2000
	ds_read_b64_tr_b16 v[248:249], v172 offset:0x2800
	ds_read_b64_tr_b16 v[250:251], v172 offset:0x3000
	ds_read_b64_tr_b16 v[252:253], v172 offset:0x3800
	s_waitcnt lgkmcnt(0)
	s_nop 0
	v_mfma_f32_32x32x16_bf16 v[0:15], v[136:139], v[238:241], v[0:15]
	ds_read_b64_tr_b16 v[238:239], v172 offset:0x200
	ds_read_b64_tr_b16 v[240:241], v172 offset:0xa00
	v_mfma_f32_32x32x16_bf16 v[0:15], v[144:147], v[242:245], v[0:15]
	ds_read_b64_tr_b16 v[242:243], v172 offset:0x1200
	ds_read_b64_tr_b16 v[244:245], v172 offset:0x1a00
	v_mfma_f32_32x32x16_bf16 v[0:15], v[220:223], v[246:249], v[0:15]
	ds_read_b64_tr_b16 v[246:247], v172 offset:0x2200
	ds_read_b64_tr_b16 v[248:249], v172 offset:0x2a00
	v_mfma_f32_32x32x16_bf16 v[0:15], v[234:237], v[250:253], v[0:15]
	ds_read_b64_tr_b16 v[250:251], v172 offset:0x3200
	ds_read_b64_tr_b16 v[252:253], v172 offset:0x3a00
	s_waitcnt lgkmcnt(0)
	v_mfma_f32_32x32x16_bf16 v[32:47], v[136:139], v[238:241], v[32:47]
	ds_read_b64_tr_b16 v[238:239], v172 offset:0x400
	ds_read_b64_tr_b16 v[240:241], v172 offset:0xc00
	v_mfma_f32_32x32x16_bf16 v[32:47], v[144:147], v[242:245], v[32:47]
	ds_read_b64_tr_b16 v[242:243], v172 offset:0x1400
	ds_read_b64_tr_b16 v[244:245], v172 offset:0x1c00
	v_mfma_f32_32x32x16_bf16 v[32:47], v[220:223], v[246:249], v[32:47]
	ds_read_b64_tr_b16 v[246:247], v172 offset:0x2400
	ds_read_b64_tr_b16 v[248:249], v172 offset:0x2c00
	v_mfma_f32_32x32x16_bf16 v[32:47], v[234:237], v[250:253], v[32:47]
	ds_read_b64_tr_b16 v[250:251], v172 offset:0x3400
	ds_read_b64_tr_b16 v[252:253], v172 offset:0x3c00
	s_waitcnt lgkmcnt(0)
	v_mfma_f32_32x32x16_bf16 v[16:31], v[136:139], v[238:241], v[16:31]
	ds_read_b64_tr_b16 v[238:239], v172 offset:0x600
	ds_read_b64_tr_b16 v[240:241], v172 offset:0xe00
	v_mfma_f32_32x32x16_bf16 v[16:31], v[144:147], v[242:245], v[16:31]
	ds_read_b64_tr_b16 v[242:243], v172 offset:0x1600
	ds_read_b64_tr_b16 v[244:245], v172 offset:0x1e00
	v_mfma_f32_32x32x16_bf16 v[16:31], v[220:223], v[246:249], v[16:31]
	ds_read_b64_tr_b16 v[246:247], v172 offset:0x2600
	ds_read_b64_tr_b16 v[248:249], v172 offset:0x2e00
	v_mfma_f32_32x32x16_bf16 v[16:31], v[234:237], v[250:253], v[16:31]
	ds_read_b64_tr_b16 v[250:251], v172 offset:0x3600
	ds_read_b64_tr_b16 v[252:253], v172 offset:0x3e00
	s_waitcnt lgkmcnt(0)
	v_mfma_f32_32x32x16_bf16 v[48:63], v[136:139], v[238:241], v[48:63]
	v_max_f32_e32 v136, v81, v81
	v_max_f32_e32 v137, v80, v80
	v_max_f32_e32 v136, v137, v136
	v_max3_f32 v136, v136, v82, v83
	v_max3_f32 v136, v136, v84, v85
	v_max3_f32 v136, v136, v86, v87
	v_max3_f32 v136, v136, v88, v89
	v_max3_f32 v136, v136, v90, v91
	v_mfma_f32_32x32x16_bf16 v[48:63], v[144:147], v[242:245], v[48:63]
	v_max3_f32 v136, v136, v92, v93
	v_max3_f32 v136, v136, v94, v95
	v_max3_f32 v136, v136, v64, v65
	v_max3_f32 v136, v136, v66, v67
	v_max3_f32 v136, v136, v68, v69
	v_max3_f32 v136, v136, v70, v71
	v_max3_f32 v136, v136, v72, v73
	v_max3_f32 v136, v136, v74, v75
	v_mfma_f32_32x32x16_bf16 v[48:63], v[220:223], v[246:249], v[48:63]
	v_max3_f32 v136, v136, v76, v77
	v_max3_f32 v136, v136, v78, v79
	v_mov_b32_e32 v137, v136
	s_nop 1
	v_permlane32_swap_b32_e32 v136, v137
	v_max_f32_e32 v137, v137, v137
	v_max_f32_e32 v136, v136, v136
	v_max_f32_e32 v136, v136, v137
	v_sub_f32_e32 v137, v136, v158
	v_cmp_ge_f32_e32 vcc, s90, v137
	v_max_f32_e32 v137, v158, v158
	v_mfma_f32_32x32x16_bf16 v[48:63], v[234:237], v[250:253], v[48:63]
	v_max_f32_e32 v136, v137, v136
	v_sub_f32_e32 v137, v158, v136
	v_exp_f32_e32 v137, v137
	s_cmp_eq_u64 vcc, exec
	s_cselect_b64 s[4:5], -1, 0
	s_barrier
	s_waitcnt vmcnt(0)
	v_cndmask_b32_e64 v234, v137, 1.0, s[4:5]
	v_cmp_gt_f32_e32 vcc, 1.0, v234
	ds_write_b128 v182, v[120:123]
	ds_write_b128 v183, v[124:127]
	ds_write_b128 v184, v[128:131] offset:32768
	ds_write_b128 v185, v[132:135] offset:32768
	s_waitcnt vmcnt(0)
	ds_write_b128 v186, v[140:143] offset:32768
	s_cbranch_vccz .LBB0_567
	s_and_saveexec_b64 s[6:7], s[2:3]
	ds_write_b32 v173, v234 offset:128
	s_or_b64 exec, exec, s[6:7]
	s_waitcnt lgkmcnt(0)
	v_add_u32_e32 v132, v169, v176
	ds_read_b128 v[120:123], v132 offset:224
	ds_read_b128 v[124:127], v132 offset:192
	ds_read_b128 v[128:131], v132 offset:160
	ds_read_b128 v[132:135], v132 offset:128
	s_waitcnt lgkmcnt(3)
	v_pk_mul_f32 v[12:13], v[12:13], v[120:121]
	s_waitcnt lgkmcnt(2)
	v_pk_mul_f32 v[8:9], v[8:9], v[124:125]
	s_waitcnt lgkmcnt(1)
	v_pk_mul_f32 v[4:5], v[4:5], v[128:129]
	v_pk_mul_f32 v[14:15], v[14:15], v[122:123]
	v_pk_mul_f32 v[10:11], v[10:11], v[126:127]
	v_pk_mul_f32 v[6:7], v[6:7], v[130:131]
	s_waitcnt lgkmcnt(0)
	v_pk_mul_f32 v[2:3], v[2:3], v[134:135]
	v_pk_mul_f32 v[0:1], v[0:1], v[132:133]
	v_pk_mul_f32 v[44:45], v[44:45], v[120:121]
	v_pk_mul_f32 v[40:41], v[40:41], v[124:125]
	v_pk_mul_f32 v[36:37], v[36:37], v[128:129]
	v_pk_mul_f32 v[46:47], v[46:47], v[122:123]
	v_pk_mul_f32 v[42:43], v[42:43], v[126:127]
	v_pk_mul_f32 v[38:39], v[38:39], v[130:131]
	v_pk_mul_f32 v[34:35], v[34:35], v[134:135]
	v_pk_mul_f32 v[32:33], v[32:33], v[132:133]
	v_pk_mul_f32 v[28:29], v[28:29], v[120:121]
	v_pk_mul_f32 v[24:25], v[24:25], v[124:125]
	v_pk_mul_f32 v[20:21], v[20:21], v[128:129]
	v_pk_mul_f32 v[30:31], v[30:31], v[122:123]
	v_pk_mul_f32 v[26:27], v[26:27], v[126:127]
	v_pk_mul_f32 v[22:23], v[22:23], v[130:131]
	v_pk_mul_f32 v[18:19], v[18:19], v[134:135]
	v_pk_mul_f32 v[16:17], v[16:17], v[132:133]
	v_pk_mul_f32 v[60:61], v[60:61], v[120:121]
	v_pk_mul_f32 v[56:57], v[56:57], v[124:125]
	v_pk_mul_f32 v[52:53], v[52:53], v[128:129]
	v_pk_mul_f32 v[62:63], v[62:63], v[122:123]
	v_pk_mul_f32 v[58:59], v[58:59], v[126:127]
	v_pk_mul_f32 v[54:55], v[54:55], v[130:131]
	v_pk_mul_f32 v[50:51], v[50:51], v[134:135]
	v_pk_mul_f32 v[48:49], v[48:49], v[132:133]
.LBB0_567:
	v_cndmask_b32_e64 v158, v136, v158, s[4:5]
	v_sub_f32_e32 v80, v80, v158
	v_sub_f32_e32 v81, v81, v158
	v_sub_f32_e32 v82, v82, v158
	v_sub_f32_e32 v83, v83, v158
	v_sub_f32_e32 v84, v84, v158
	v_sub_f32_e32 v85, v85, v158
	v_sub_f32_e32 v86, v86, v158
	v_sub_f32_e32 v87, v87, v158
	v_sub_f32_e32 v88, v88, v158
	v_sub_f32_e32 v89, v89, v158
	v_sub_f32_e32 v90, v90, v158
	v_sub_f32_e32 v91, v91, v158
	v_sub_f32_e32 v92, v92, v158
	v_sub_f32_e32 v93, v93, v158
	v_sub_f32_e32 v94, v94, v158
	v_sub_f32_e32 v95, v95, v158
	v_sub_f32_e32 v232, v76, v158
	v_sub_f32_e32 v235, v77, v158
	v_sub_f32_e32 v236, v78, v158
	v_exp_f32_e32 v133, v80
	v_exp_f32_e32 v135, v81
	v_exp_f32_e32 v131, v82
	v_exp_f32_e32 v134, v83
	v_exp_f32_e32 v130, v84
	v_exp_f32_e32 v132, v85
	v_exp_f32_e32 v128, v86
	v_exp_f32_e32 v129, v87
	v_exp_f32_e32 v125, v88
	v_exp_f32_e32 v127, v89
	v_exp_f32_e32 v124, v90
	v_exp_f32_e32 v126, v91
	v_exp_f32_e32 v121, v92
	v_exp_f32_e32 v123, v93
	v_exp_f32_e32 v120, v94
	v_exp_f32_e32 v122, v95
	v_sub_f32_e32 v178, v64, v158
	v_sub_f32_e32 v179, v65, v158
	v_sub_f32_e32 v213, v66, v158
	v_sub_f32_e32 v220, v67, v158
	v_sub_f32_e32 v221, v68, v158
	v_sub_f32_e32 v222, v69, v158
	v_sub_f32_e32 v223, v70, v158
	v_sub_f32_e32 v226, v71, v158
	v_sub_f32_e32 v227, v72, v158
	v_sub_f32_e32 v228, v73, v158
	v_sub_f32_e32 v229, v74, v158
	v_sub_f32_e32 v230, v75, v158
	v_sub_f32_e32 v237, v79, v158
	s_waitcnt lgkmcnt(0)
	s_barrier
	ds_read_b128 v[64:67], v187 offset:32768
	ds_read_b128 v[68:71], v187 offset:45056
	ds_read_b128 v[136:139], v189 offset:32768
	ds_read_b128 v[140:143], v189 offset:45056
	v_exp_f32_e32 v241, v236
	v_exp_f32_e32 v237, v237
	s_waitcnt lgkmcnt(3)
	v_mfma_f32_32x32x16_bf16 v[80:95], v[64:67], v[96:99], 0
	s_waitcnt lgkmcnt(2)
	v_mfma_f32_32x32x16_bf16 v[64:79], v[68:71], v[96:99], 0
	s_waitcnt lgkmcnt(1)
	v_mfma_f32_32x32x16_bf16 v[80:95], v[136:139], v[100:103], v[80:95]
	s_waitcnt lgkmcnt(0)
	v_mfma_f32_32x32x16_bf16 v[64:79], v[140:143], v[100:103], v[64:79]
	ds_read_b128 v[136:139], v190 offset:32768
	ds_read_b128 v[140:143], v190 offset:45056
	s_waitcnt lgkmcnt(1)
	v_mfma_f32_32x32x16_bf16 v[80:95], v[136:139], v[104:107], v[80:95]
	s_waitcnt lgkmcnt(0)
	v_mfma_f32_32x32x16_bf16 v[64:79], v[140:143], v[104:107], v[64:79]
	ds_read_b128 v[136:139], v191 offset:32768
	ds_read_b128 v[140:143], v191 offset:45056
	s_waitcnt lgkmcnt(1)
	v_mfma_f32_32x32x16_bf16 v[80:95], v[136:139], v[108:111], v[80:95]
	s_waitcnt lgkmcnt(0)
	v_mfma_f32_32x32x16_bf16 v[64:79], v[140:143], v[108:111], v[64:79]
	ds_read_b128 v[136:139], v192 offset:32768
	ds_read_b128 v[140:143], v192 offset:45056
	s_waitcnt lgkmcnt(1)
	v_mfma_f32_32x32x16_bf16 v[80:95], v[136:139], v[112:115], v[80:95]
	s_waitcnt lgkmcnt(0)
	v_mfma_f32_32x32x16_bf16 v[64:79], v[140:143], v[112:115], v[64:79]
	ds_read_b128 v[136:139], v193 offset:32768
	ds_read_b128 v[140:143], v193 offset:45056
	s_waitcnt lgkmcnt(1)
	v_mfma_f32_32x32x16_bf16 v[80:95], v[136:139], v[116:119], v[80:95]
	s_waitcnt lgkmcnt(0)
	v_mfma_f32_32x32x16_bf16 v[64:79], v[140:143], v[116:119], v[64:79]
	ds_read_b128 v[136:139], v194 offset:32768
	ds_read_b128 v[140:143], v194 offset:45056
	ds_read_b128 v[144:147], v171
	s_waitcnt lgkmcnt(0)
	v_mfma_f32_32x32x16_bf16 v[80:95], v[136:139], v[144:147], v[80:95]
	v_mfma_f32_32x32x16_bf16 v[64:79], v[140:143], v[144:147], v[64:79]
	ds_read_b128 v[136:139], v195 offset:32768
	ds_read_b128 v[140:143], v195 offset:45056
	ds_read_b128 v[144:147], v171 offset:1024
	s_waitcnt lgkmcnt(0)
	v_mfma_f32_32x32x16_bf16 v[80:95], v[136:139], v[144:147], v[80:95]
	v_mfma_f32_32x32x16_bf16 v[64:79], v[140:143], v[144:147], v[64:79]
	ds_read_b128 v[136:139], v196 offset:32768
	ds_read_b128 v[140:143], v196 offset:45056
	ds_read_b128 v[144:147], v171 offset:2048
	s_waitcnt lgkmcnt(0)
	v_mfma_f32_32x32x16_bf16 v[80:95], v[136:139], v[144:147], v[80:95]
	v_mfma_f32_32x32x16_bf16 v[64:79], v[140:143], v[144:147], v[64:79]
	ds_read_b128 v[136:139], v197 offset:32768
	ds_read_b128 v[140:143], v197 offset:45056
	ds_read_b128 v[144:147], v171 offset:3072
	s_waitcnt lgkmcnt(0)
	v_mfma_f32_32x32x16_bf16 v[80:95], v[136:139], v[144:147], v[80:95]
	v_mfma_f32_32x32x16_bf16 v[64:79], v[140:143], v[144:147], v[64:79]
	ds_read_b128 v[136:139], v199 offset:32768
	ds_read_b128 v[140:143], v199 offset:45056
	ds_read_b128 v[144:147], v171 offset:4096
	s_waitcnt lgkmcnt(0)
	v_mfma_f32_32x32x16_bf16 v[80:95], v[136:139], v[144:147], v[80:95]
	v_mfma_f32_32x32x16_bf16 v[64:79], v[140:143], v[144:147], v[64:79]
	ds_read_b128 v[136:139], v198 offset:32768
	ds_read_b128 v[140:143], v198 offset:45056
	ds_read_b128 v[144:147], v171 offset:5120
	s_waitcnt lgkmcnt(0)
	v_mfma_f32_32x32x16_bf16 v[80:95], v[136:139], v[144:147], v[80:95]
	v_add_f32_e32 v136, 0, v133
	v_add_f32_e32 v136, v135, v136
	v_add_f32_e32 v136, v131, v136
	v_add_f32_e32 v136, v134, v136
	v_add_f32_e32 v136, v130, v136
	v_add_f32_e32 v136, v132, v136
	v_add_f32_e32 v136, v128, v136
	v_add_f32_e32 v136, v129, v136
	v_add_f32_e32 v136, v125, v136
	v_add_f32_e32 v136, v127, v136
	v_add_f32_e32 v136, v124, v136
	v_add_f32_e32 v136, v126, v136
	v_mfma_f32_32x32x16_bf16 v[64:79], v[140:143], v[144:147], v[64:79]
	v_exp_f32_e32 v140, v178
	v_add_f32_e32 v136, v121, v136
	v_exp_f32_e32 v141, v179
	v_add_f32_e32 v136, v123, v136
	v_exp_f32_e32 v142, v213
	v_add_f32_e32 v136, v120, v136
	v_exp_f32_e32 v143, v220
	v_add_f32_e32 v136, v122, v136
	v_exp_f32_e32 v178, v221
	v_add_f32_e32 v136, v140, v136
	v_exp_f32_e32 v179, v222
	v_add_f32_e32 v136, v141, v136
	v_exp_f32_e32 v213, v223
	v_add_f32_e32 v136, v142, v136
	v_exp_f32_e32 v223, v226
	v_add_f32_e32 v136, v143, v136
	v_exp_f32_e32 v226, v227
	v_add_f32_e32 v136, v178, v136
	v_exp_f32_e32 v227, v228
	v_add_f32_e32 v136, v179, v136
	v_exp_f32_e32 v228, v229
	v_add_f32_e32 v136, v213, v136
	v_exp_f32_e32 v229, v230
	v_add_f32_e32 v136, v223, v136
	v_exp_f32_e32 v230, v232
	v_add_f32_e32 v136, v226, v136
	v_exp_f32_e32 v232, v235
	v_add_f32_e32 v136, v227, v136
	v_add_f32_e32 v136, v228, v136
	v_add_f32_e32 v136, v229, v136
	v_add_f32_e32 v136, v230, v136
	v_add_f32_e32 v136, v232, v136
	v_add_f32_e32 v136, v241, v136
	v_add_f32_e32 v235, v237, v136
	v_mov_b32_e32 v236, v235
	v_cvt_pk_bf16_f32 v136, v133, v135
	v_cvt_pk_bf16_f32 v137, v131, v134
	v_cvt_pk_bf16_f32 v138, v130, v132
	s_nop 1
	v_permlane32_swap_b32_e32 v235, v236
	v_cvt_pk_bf16_f32 v139, v128, v129
	v_permlane32_swap_b32_e32 v136, v138
	v_cvt_pk_bf16_f32 v144, v125, v127
	v_cvt_pk_bf16_f32 v145, v124, v126
	v_cvt_pk_bf16_f32 v146, v121, v123
	v_cvt_pk_bf16_f32 v147, v120, v122
	v_cvt_pk_bf16_f32 v220, v140, v141
	v_cvt_pk_bf16_f32 v221, v142, v143
	v_cvt_pk_bf16_f32 v222, v178, v179
	v_cvt_pk_bf16_f32 v223, v213, v223
	v_cvt_pk_bf16_f32 v238, v226, v227
	v_cvt_pk_bf16_f32 v239, v228, v229
	v_cvt_pk_bf16_f32 v240, v230, v232
	v_cvt_pk_bf16_f32 v241, v241, v237
	v_permlane32_swap_b32_e32 v137, v139
	v_permlane32_swap_b32_e32 v144, v146
	v_permlane32_swap_b32_e32 v145, v147
	v_permlane32_swap_b32_e32 v220, v222
	v_permlane32_swap_b32_e32 v221, v223
	v_permlane32_swap_b32_e32 v238, v240
	v_permlane32_swap_b32_e32 v239, v241
	s_add_i32 s4, s15, 64
	s_cmp_lt_u32 s16, 2
	s_cselect_b32 s4, s4, s14
	s_ashr_i32 s5, s4, 31
	s_lshl_b64 s[76:77], s[4:5], 11
	s_mul_hi_i32 s79, s4, s87
	s_mul_i32 s78, s4, s87
	v_lshl_add_u64 v[120:121], v[148:149], 0, s[76:77]
	v_lshl_add_u64 v[124:125], v[156:157], 0, s[76:77]
	v_lshl_add_u64 v[130:131], v[150:151], 0, s[78:79]
	v_lshl_add_u64 v[134:135], v[152:153], 0, s[78:79]
	v_lshl_add_u64 v[140:141], v[154:155], 0, s[78:79]
	global_load_dwordx4 v[120:123], v[120:121], off
	global_load_dwordx4 v[124:127], v[124:125], off
	global_load_dwordx4 v[128:131], v[130:131], off
	global_load_dwordx4 v[132:135], v[134:135], off
	global_load_dwordx4 v[140:143], v[140:141], off
	ds_read_b64_tr_b16 v[242:243], v175 offset:0
	ds_read_b64_tr_b16 v[244:245], v175 offset:0x800
	ds_read_b64_tr_b16 v[246:247], v175 offset:0x1000
	ds_read_b64_tr_b16 v[248:249], v175 offset:0x1800
	ds_read_b64_tr_b16 v[250:251], v175 offset:0x2000
	ds_read_b64_tr_b16 v[252:253], v175 offset:0x2800
	ds_read_b64_tr_b16 v[226:227], v175 offset:0x3000
	ds_read_b64_tr_b16 v[228:229], v175 offset:0x3800
	s_waitcnt lgkmcnt(0)
	s_nop 0
	v_mfma_f32_32x32x16_bf16 v[0:15], v[136:139], v[242:245], v[0:15]
	v_mfma_f32_32x32x16_bf16 v[0:15], v[144:147], v[246:249], v[0:15]
	v_mfma_f32_32x32x16_bf16 v[0:15], v[220:223], v[250:253], v[0:15]
	v_mfma_f32_32x32x16_bf16 v[0:15], v[238:241], v[226:229], v[0:15]
	ds_read_b64_tr_b16 v[226:227], v175 offset:0x200
	ds_read_b64_tr_b16 v[228:229], v175 offset:0xa00
	ds_read_b64_tr_b16 v[242:243], v175 offset:0x1200
	ds_read_b64_tr_b16 v[244:245], v175 offset:0x1a00
	ds_read_b64_tr_b16 v[246:247], v175 offset:0x2200
	ds_read_b64_tr_b16 v[248:249], v175 offset:0x2a00
	ds_read_b64_tr_b16 v[250:251], v175 offset:0x3200
	ds_read_b64_tr_b16 v[252:253], v175 offset:0x3a00
	s_waitcnt lgkmcnt(0)
	s_nop 0
	v_mfma_f32_32x32x16_bf16 v[32:47], v[136:139], v[226:229], v[32:47]
	ds_read_b64_tr_b16 v[226:227], v175 offset:0x400
	ds_read_b64_tr_b16 v[228:229], v175 offset:0xc00
	v_mfma_f32_32x32x16_bf16 v[32:47], v[144:147], v[242:245], v[32:47]
	ds_read_b64_tr_b16 v[242:243], v175 offset:0x1400
	ds_read_b64_tr_b16 v[244:245], v175 offset:0x1c00
	v_mfma_f32_32x32x16_bf16 v[32:47], v[220:223], v[246:249], v[32:47]
	ds_read_b64_tr_b16 v[246:247], v175 offset:0x2400
	ds_read_b64_tr_b16 v[248:249], v175 offset:0x2c00
	v_mfma_f32_32x32x16_bf16 v[32:47], v[238:241], v[250:253], v[32:47]
	ds_read_b64_tr_b16 v[250:251], v175 offset:0x3400
	ds_read_b64_tr_b16 v[252:253], v175 offset:0x3c00
	s_waitcnt lgkmcnt(0)
	v_mfma_f32_32x32x16_bf16 v[16:31], v[136:139], v[226:229], v[16:31]
	ds_read_b64_tr_b16 v[226:227], v175 offset:0x600
	ds_read_b64_tr_b16 v[228:229], v175 offset:0xe00
	v_mfma_f32_32x32x16_bf16 v[16:31], v[144:147], v[242:245], v[16:31]
	ds_read_b64_tr_b16 v[242:243], v175 offset:0x1600
	ds_read_b64_tr_b16 v[244:245], v175 offset:0x1e00
	v_mfma_f32_32x32x16_bf16 v[16:31], v[220:223], v[246:249], v[16:31]
	ds_read_b64_tr_b16 v[246:247], v175 offset:0x2600
	ds_read_b64_tr_b16 v[248:249], v175 offset:0x2e00
	v_mfma_f32_32x32x16_bf16 v[16:31], v[238:241], v[250:253], v[16:31]
	ds_read_b64_tr_b16 v[250:251], v175 offset:0x3600
	ds_read_b64_tr_b16 v[252:253], v175 offset:0x3e00
	s_waitcnt lgkmcnt(0)
	v_mfma_f32_32x32x16_bf16 v[48:63], v[136:139], v[226:229], v[48:63]
	v_max_f32_e32 v136, v81, v81
	v_max_f32_e32 v137, v80, v80
	v_max_f32_e32 v136, v137, v136
	v_max3_f32 v136, v136, v82, v83
	v_max3_f32 v136, v136, v84, v85
	v_max3_f32 v136, v136, v86, v87
	v_max3_f32 v136, v136, v88, v89
	v_max3_f32 v136, v136, v90, v91
	v_mfma_f32_32x32x16_bf16 v[48:63], v[144:147], v[242:245], v[48:63]
	v_max3_f32 v136, v136, v92, v93
	v_max3_f32 v136, v136, v94, v95
	v_max3_f32 v136, v136, v64, v65
	v_max3_f32 v136, v136, v66, v67
	v_max3_f32 v136, v136, v68, v69
	v_max3_f32 v136, v136, v70, v71
	v_max3_f32 v136, v136, v72, v73
	v_max3_f32 v136, v136, v74, v75
	v_mfma_f32_32x32x16_bf16 v[48:63], v[220:223], v[246:249], v[48:63]
	v_max3_f32 v136, v136, v76, v77
	v_max3_f32 v136, v136, v78, v79
	v_mov_b32_e32 v137, v136
	s_nop 1
	v_permlane32_swap_b32_e32 v136, v137
	v_max_f32_e32 v137, v137, v137
	v_max_f32_e32 v136, v136, v136
	v_max_f32_e32 v136, v136, v137
	v_sub_f32_e32 v137, v136, v158
	v_cmp_ge_f32_e32 vcc, s90, v137
	v_max_f32_e32 v137, v158, v158
	v_mfma_f32_32x32x16_bf16 v[48:63], v[238:241], v[250:253], v[48:63]
	v_max_f32_e32 v136, v137, v136
	v_sub_f32_e32 v137, v158, v136
	v_exp_f32_e32 v137, v137
	s_cmp_eq_u64 vcc, exec
	s_cselect_b64 s[4:5], -1, 0
	s_barrier
	s_waitcnt vmcnt(0)
	v_cndmask_b32_e64 v232, v137, 1.0, s[4:5]
	v_cmp_gt_f32_e32 vcc, 1.0, v232
	ds_write_b128 v182, v[120:123] offset:16384
	ds_write_b128 v183, v[124:127] offset:16384
	ds_write_b128 v184, v[128:131] offset:57344
	ds_write_b128 v185, v[132:135] offset:57344
	s_waitcnt vmcnt(0)
	ds_write_b128 v186, v[140:143] offset:57344
	s_cbranch_vccz .LBB0_571
	s_and_saveexec_b64 s[6:7], s[2:3]
	ds_write_b32 v173, v232 offset:128
	s_or_b64 exec, exec, s[6:7]
	s_waitcnt lgkmcnt(0)
	v_add_u32_e32 v132, v169, v176
	ds_read_b128 v[120:123], v132 offset:224
	ds_read_b128 v[124:127], v132 offset:192
	ds_read_b128 v[128:131], v132 offset:160
	ds_read_b128 v[132:135], v132 offset:128
	s_waitcnt lgkmcnt(3)
	v_pk_mul_f32 v[12:13], v[12:13], v[120:121]
	s_waitcnt lgkmcnt(2)
	v_pk_mul_f32 v[8:9], v[8:9], v[124:125]
	s_waitcnt lgkmcnt(1)
	v_pk_mul_f32 v[4:5], v[4:5], v[128:129]
	v_pk_mul_f32 v[14:15], v[14:15], v[122:123]
	v_pk_mul_f32 v[10:11], v[10:11], v[126:127]
	v_pk_mul_f32 v[6:7], v[6:7], v[130:131]
	s_waitcnt lgkmcnt(0)
	v_pk_mul_f32 v[2:3], v[2:3], v[134:135]
	v_pk_mul_f32 v[0:1], v[0:1], v[132:133]
	v_pk_mul_f32 v[44:45], v[44:45], v[120:121]
	v_pk_mul_f32 v[40:41], v[40:41], v[124:125]
	v_pk_mul_f32 v[36:37], v[36:37], v[128:129]
	v_pk_mul_f32 v[46:47], v[46:47], v[122:123]
	v_pk_mul_f32 v[42:43], v[42:43], v[126:127]
	v_pk_mul_f32 v[38:39], v[38:39], v[130:131]
	v_pk_mul_f32 v[34:35], v[34:35], v[134:135]
	v_pk_mul_f32 v[32:33], v[32:33], v[132:133]
	v_pk_mul_f32 v[28:29], v[28:29], v[120:121]
	v_pk_mul_f32 v[24:25], v[24:25], v[124:125]
	v_pk_mul_f32 v[20:21], v[20:21], v[128:129]
	v_pk_mul_f32 v[30:31], v[30:31], v[122:123]
	v_pk_mul_f32 v[26:27], v[26:27], v[126:127]
	v_pk_mul_f32 v[22:23], v[22:23], v[130:131]
	v_pk_mul_f32 v[18:19], v[18:19], v[134:135]
	v_pk_mul_f32 v[16:17], v[16:17], v[132:133]
	v_pk_mul_f32 v[60:61], v[60:61], v[120:121]
	v_pk_mul_f32 v[56:57], v[56:57], v[124:125]
	v_pk_mul_f32 v[52:53], v[52:53], v[128:129]
	v_pk_mul_f32 v[62:63], v[62:63], v[122:123]
	v_pk_mul_f32 v[58:59], v[58:59], v[126:127]
	v_pk_mul_f32 v[54:55], v[54:55], v[130:131]
	v_pk_mul_f32 v[50:51], v[50:51], v[134:135]
	v_pk_mul_f32 v[48:49], v[48:49], v[132:133]
